# branch-free top-k compaction loop; layer-0 seam on the XCD barrier with parallel census loads
# speedup vs baseline: 1.0607x; 1.0085x over previous
.LBB0_144:
	s_or_b64 exec, exec, s[0:1]
	s_and_b64 vcc, exec, s[84:85]
	v_cmp_eq_u32_e64 s[36:37], 0, v180
	s_waitcnt vmcnt(0)
	v_readlane_b32 s0, v252, 37
	v_readlane_b32 s1, v252, 38
	s_and_b64 s[36:37], s[0:1], s[36:37]
	s_barrier
	s_and_saveexec_b64 s[0:1], s[36:37]
	s_cbranch_execz .LBB0_198
	v_readlane_b32 s4, v250, 15
	s_waitcnt vmcnt(0) expcnt(0) lgkmcnt(0)
	s_nop 0
	v_mov_b32_e32 v0, s4
	ds_read_b32 v2, v0
	v_readlane_b32 s4, v250, 16
	s_waitcnt lgkmcnt(0)
	v_cmp_ne_u32_e32 vcc, 0, v2
	v_mov_b32_e32 v0, s4
	ds_read_b32 v0, v0
	s_cbranch_vccnz .LBB0_162
	s_mov_b32 s42, 1
	s_branch .LBB0_149

.LBB0_149:
	v_readlane_b32 s4, v252, 42
	v_readlane_b32 s5, v252, 43
	s_mov_b64 s[36:37], -1
	s_mov_b64 s[38:39], -1
	s_waitcnt lgkmcnt(0)
	s_nop 1
	global_load_dword v0, v169, s[4:5] sc1
	v_readlane_b32 s4, v252, 44
	v_readlane_b32 s5, v252, 45
	s_nop 4
	global_load_dword v1, v169, s[4:5] sc1
	v_readlane_b32 s4, v252, 46
	v_readlane_b32 s5, v252, 47
	s_nop 1
	s_nop 2
	global_load_dword v2, v169, s[4:5] sc1
	v_readlane_b32 s4, v252, 48
	v_readlane_b32 s5, v252, 49
	s_nop 1
	s_nop 2
	global_load_dword v3, v169, s[4:5] sc1
	v_readlane_b32 s4, v252, 50
	v_readlane_b32 s5, v252, 51
	s_nop 1
	s_nop 2
	global_load_dword v4, v169, s[4:5] sc1
	v_readlane_b32 s4, v252, 52
	v_readlane_b32 s5, v252, 53
	s_nop 1
	s_nop 2
	global_load_dword v5, v169, s[4:5] sc1
	v_readlane_b32 s4, v252, 54
	v_readlane_b32 s5, v252, 55
	s_nop 1
	s_nop 2
	global_load_dword v6, v169, s[4:5] sc1
	v_readlane_b32 s4, v252, 56
	v_readlane_b32 s5, v252, 57
	s_nop 1
	s_nop 2
	global_load_dword v7, v169, s[4:5] sc1
	v_readlane_b32 s4, v252, 58
	v_readlane_b32 s5, v252, 59
	s_nop 1
	s_nop 2
	global_load_dword v8, v169, s[4:5] sc1
	v_readlane_b32 s4, v252, 60
	v_readlane_b32 s5, v252, 61
	s_nop 1
	s_nop 2
	global_load_dword v9, v169, s[4:5] sc1
	v_readlane_b32 s4, v252, 62
	v_readlane_b32 s5, v252, 63
	s_nop 1
	s_nop 2
	global_load_dword v10, v169, s[4:5] sc1
	v_readlane_b32 s4, v251, 0
	v_readlane_b32 s5, v251, 1
	s_nop 1
	s_nop 2
	global_load_dword v11, v169, s[4:5] sc1
	v_readlane_b32 s4, v251, 2
	v_readlane_b32 s5, v251, 3
	s_nop 1
	s_nop 2
	global_load_dword v12, v169, s[4:5] sc1
	v_readlane_b32 s4, v251, 4
	v_readlane_b32 s5, v251, 5
	s_nop 1
	s_nop 2
	global_load_dword v13, v169, s[4:5] sc1
	v_readlane_b32 s4, v251, 6
	v_readlane_b32 s5, v251, 7
	s_nop 1
	s_nop 2
	global_load_dword v14, v169, s[4:5] sc1
	v_readlane_b32 s4, v251, 8
	v_readlane_b32 s5, v251, 9
	s_nop 1
	s_nop 2
	global_load_dword v15, v169, s[4:5] sc1
	v_readlane_b32 s4, v252, 39
	s_nop 1
	s_waitcnt vmcnt(0)
	v_add_u32_e32 v16, v1, v0
	v_add_u32_e32 v16, v16, v2
	v_add_u32_e32 v16, v16, v3
	v_add_u32_e32 v16, v16, v4
	v_add_u32_e32 v16, v16, v5
	v_add_u32_e32 v16, v16, v6
	v_add_u32_e32 v16, v16, v7
	v_add_u32_e32 v16, v16, v8
	v_add_u32_e32 v16, v16, v9
	v_add_u32_e32 v16, v16, v10
	v_add_u32_e32 v16, v16, v11
	v_add_u32_e32 v16, v16, v12
	v_add_u32_e32 v16, v16, v13
	v_add_u32_e32 v16, v16, v14
	v_add_u32_e32 v16, v16, v15
	v_cmp_eq_u32_e32 vcc, s4, v16
	s_cbranch_vccnz .LBB0_148
	s_and_b32 s36, s42, 0xff
	s_cmp_eq_u32 s36, 0
	s_mov_b64 s[36:37], -1
	s_mov_b64 s[40:41], -1
	s_sleep 1
	s_cbranch_scc0 .LBB0_153
	v_readlane_b32 s4, v252, 40
	v_readlane_b32 s5, v252, 41
	s_nop 4
	global_load_dword v16, v169, s[4:5] sc1
	s_waitcnt vmcnt(0)
	v_cmp_eq_u32_e32 vcc, 0, v16
	s_cbranch_vccnz .LBB0_155
	s_mov_b64 s[40:41], 0

.LBB0_444:
	ds_read2st64_b32 v[2:3], v9 offset1:1
	ds_read2st64_b32 v[0:1], v9 offset0:2 offset1:3
	v_add_u32_e32 v5, 4, v5
	s_movk_i32 s15, 0x200
	v_cmp_ge_u32_e64 s[58:59], v5, v6
	s_waitcnt lgkmcnt(1)
	v_lshrrev_b32_e32 v244, 21, v2
	v_cmp_gt_u32_e64 s[44:45], v244, v7
	v_cmp_eq_u32_e64 s[46:47], v244, v7
	v_mov_b32_e32 v247, v8
	s_nop 0
	v_mbcnt_lo_u32_b32 v245, s44, 0
	v_mbcnt_hi_u32_b32 v245, s45, v245
	v_mbcnt_lo_u32_b32 v246, s46, 0
	v_mbcnt_hi_u32_b32 v246, s47, v246
	v_add_u32_e32 v245, s36, v245
	v_sub_u32_e32 v248, 0xff, v245
	v_cndmask_b32_e64 v245, v248, v245, s[40:41]
	v_lshl_add_u32 v245, v245, 2, v186
	v_add_u32_e32 v246, s37, v246
	v_cmp_gt_i32_e64 s[48:49], s15, v246
	v_lshl_add_u32 v246, v246, 2, v188
	s_mov_b64 exec, s[44:45]
	ds_write_b32 v245, v247
	s_and_b64 exec, s[46:47], s[48:49]
	ds_write_b32 v246, v247
	s_mov_b64 exec, -1
	s_bcnt1_i32_b64 s44, s[44:45]
	s_bcnt1_i32_b64 s46, s[46:47]
	s_add_i32 s36, s36, s44
	s_add_i32 s37, s37, s46
	v_lshrrev_b32_e32 v244, 21, v3
	v_cmp_gt_u32_e64 s[44:45], v244, v7
	v_cmp_eq_u32_e64 s[46:47], v244, v7
	v_add_u32_e32 v247, 0x40, v8
	s_nop 0
	v_mbcnt_lo_u32_b32 v245, s44, 0
	v_mbcnt_hi_u32_b32 v245, s45, v245
	v_mbcnt_lo_u32_b32 v246, s46, 0
	v_mbcnt_hi_u32_b32 v246, s47, v246
	v_add_u32_e32 v245, s36, v245
	v_sub_u32_e32 v248, 0xff, v245
	v_cndmask_b32_e64 v245, v248, v245, s[40:41]
	v_lshl_add_u32 v245, v245, 2, v186
	v_add_u32_e32 v246, s37, v246
	v_cmp_gt_i32_e64 s[48:49], s15, v246
	v_lshl_add_u32 v246, v246, 2, v188
	s_mov_b64 exec, s[44:45]
	ds_write_b32 v245, v247
	s_and_b64 exec, s[46:47], s[48:49]
	ds_write_b32 v246, v247
	s_mov_b64 exec, -1
	s_bcnt1_i32_b64 s44, s[44:45]
	s_bcnt1_i32_b64 s46, s[46:47]
	s_add_i32 s36, s36, s44
	s_add_i32 s37, s37, s46
	s_waitcnt lgkmcnt(0)
	v_lshrrev_b32_e32 v244, 21, v0
	v_cmp_gt_u32_e64 s[44:45], v244, v7
	v_cmp_eq_u32_e64 s[46:47], v244, v7
	v_add_u32_e32 v247, 0x80, v8
	s_nop 0
	v_mbcnt_lo_u32_b32 v245, s44, 0
	v_mbcnt_hi_u32_b32 v245, s45, v245
	v_mbcnt_lo_u32_b32 v246, s46, 0
	v_mbcnt_hi_u32_b32 v246, s47, v246
	v_add_u32_e32 v245, s36, v245
	v_sub_u32_e32 v248, 0xff, v245
	v_cndmask_b32_e64 v245, v248, v245, s[40:41]
	v_lshl_add_u32 v245, v245, 2, v186
	v_add_u32_e32 v246, s37, v246
	v_cmp_gt_i32_e64 s[48:49], s15, v246
	v_lshl_add_u32 v246, v246, 2, v188
	s_mov_b64 exec, s[44:45]
	ds_write_b32 v245, v247
	s_and_b64 exec, s[46:47], s[48:49]
	ds_write_b32 v246, v247
	s_mov_b64 exec, -1
	s_bcnt1_i32_b64 s44, s[44:45]
	s_bcnt1_i32_b64 s46, s[46:47]
	s_add_i32 s36, s36, s44
	s_add_i32 s37, s37, s46
	v_lshrrev_b32_e32 v244, 21, v1
	v_cmp_gt_u32_e64 s[44:45], v244, v7
	v_cmp_eq_u32_e64 s[46:47], v244, v7
	v_add_u32_e32 v247, 0xc0, v8
	s_nop 0
	v_mbcnt_lo_u32_b32 v245, s44, 0
	v_mbcnt_hi_u32_b32 v245, s45, v245
	v_mbcnt_lo_u32_b32 v246, s46, 0
	v_mbcnt_hi_u32_b32 v246, s47, v246
	v_add_u32_e32 v245, s36, v245
	v_sub_u32_e32 v248, 0xff, v245
	v_cndmask_b32_e64 v245, v248, v245, s[40:41]
	v_lshl_add_u32 v245, v245, 2, v186
	v_add_u32_e32 v246, s37, v246
	v_cmp_gt_i32_e64 s[48:49], s15, v246
	v_lshl_add_u32 v246, v246, 2, v188
	s_mov_b64 exec, s[44:45]
	ds_write_b32 v245, v247
	s_and_b64 exec, s[46:47], s[48:49]
	ds_write_b32 v246, v247
	s_mov_b64 exec, -1
	s_bcnt1_i32_b64 s44, s[44:45]
	s_bcnt1_i32_b64 s46, s[46:47]
	s_add_i32 s36, s36, s44
	s_add_i32 s37, s37, s46
	v_add_u32_e32 v8, 0x100, v8
	v_add_u32_e32 v9, 0x400, v9
	s_cmp_lg_u64 s[58:59], 0
	s_cbranch_scc0 .LBB0_444
	v_mov_b32_e32 v2, s36
	v_mov_b32_e32 v3, s37
